# v74: early acquire - L1 invalidate (buffer_inv sc1) hoisted to the arrival of the 4 XCD-local seams, overlapping the arrive round trip; no wait for release-atomic ack
# speedup vs baseline: 1.0040x; 1.0040x over previous
.LBB0_246:
	s_or_b64 exec, exec, s[20:21]
	buffer_inv sc1
	s_waitcnt vmcnt(0)
	v_readfirstlane_b32 s18, v2
	s_waitcnt lgkmcnt(0)
	v_cvt_f32_u32_e32 v2, v0
	v_sub_u32_e32 v3, 0, v0
	v_add_u32_e32 v1, s18, v1
	v_readlane_b32 s18, v252, 58
	v_rcp_iflag_f32_e32 v2, v2
	v_readlane_b32 s19, v252, 59
	s_mov_b64 s[20:21], -1
	v_mul_f32_e32 v2, 0x4f7ffffe, v2
	v_cvt_u32_f32_e32 v2, v2
	v_mul_lo_u32 v3, v3, v2
	v_mul_hi_u32 v3, v2, v3
	v_add_u32_e32 v2, v2, v3
	v_mul_hi_u32 v2, v1, v2
	v_mul_lo_u32 v3, v2, v0
	v_sub_u32_e32 v3, v1, v3
	v_cmp_ge_u32_e32 vcc, v3, v0
	v_add_u32_e32 v4, 1, v2
	v_add_u32_e32 v1, 1, v1
	v_cndmask_b32_e32 v2, v2, v4, vcc
	v_sub_u32_e32 v4, v3, v0
	v_cndmask_b32_e32 v3, v3, v4, vcc
	v_cmp_ge_u32_e32 vcc, v3, v0
	v_add_u32_e32 v3, 1, v2
	s_nop 0
	v_cndmask_b32_e32 v2, v2, v3, vcc
	v_mul_lo_u32 v3, v0, v2
	v_add_u32_e32 v0, v3, v0
	v_cmp_ne_u32_e32 vcc, v1, v0
	v_mov_b64_e32 v[0:1], s[18:19]
	s_and_saveexec_b64 s[18:19], vcc
	s_cbranch_execz .LBB0_258
	v_readlane_b32 s20, v252, 58
	v_readlane_b32 s21, v252, 59
	s_mov_b64 s[44:45], 0
	s_nop 3
	global_load_dword v0, v153, s[20:21] sc1
	s_waitcnt vmcnt(0)
	v_cmp_eq_u32_e32 vcc, v0, v2
	s_and_saveexec_b64 s[20:21], vcc
	s_cbranch_execz .LBB0_257
	s_mov_b32 s62, 1
	s_branch .LBB0_250

.LBB0_260:
	s_or_b64 exec, exec, s[18:19]
.LBB0_261:
	s_or_b64 exec, exec, s[0:1]
	s_barrier

.LBB0_383:
	s_or_b64 exec, exec, s[18:19]
	buffer_inv sc1
	s_waitcnt vmcnt(0)
	v_readfirstlane_b32 s16, v2
	s_waitcnt lgkmcnt(0)
	v_cvt_f32_u32_e32 v2, v0
	v_sub_u32_e32 v3, 0, v0
	v_add_u32_e32 v1, s16, v1
	v_readlane_b32 s16, v252, 58
	v_rcp_iflag_f32_e32 v2, v2
	v_readlane_b32 s17, v252, 59
	s_mov_b64 s[18:19], -1
	v_mul_f32_e32 v2, 0x4f7ffffe, v2
	v_cvt_u32_f32_e32 v2, v2
	v_mul_lo_u32 v3, v3, v2
	v_mul_hi_u32 v3, v2, v3
	v_add_u32_e32 v2, v2, v3
	v_mul_hi_u32 v2, v1, v2
	v_mul_lo_u32 v3, v2, v0
	v_sub_u32_e32 v3, v1, v3
	v_cmp_ge_u32_e32 vcc, v3, v0
	v_add_u32_e32 v4, 1, v2
	v_add_u32_e32 v1, 1, v1
	v_cndmask_b32_e32 v2, v2, v4, vcc
	v_sub_u32_e32 v4, v3, v0
	v_cndmask_b32_e32 v3, v3, v4, vcc
	v_cmp_ge_u32_e32 vcc, v3, v0
	v_add_u32_e32 v3, 1, v2
	s_nop 0
	v_cndmask_b32_e32 v2, v2, v3, vcc
	v_mul_lo_u32 v3, v0, v2
	v_add_u32_e32 v0, v3, v0
	v_cmp_ne_u32_e32 vcc, v1, v0
	v_mov_b64_e32 v[0:1], s[16:17]
	s_and_saveexec_b64 s[16:17], vcc
	s_cbranch_execz .LBB0_395
	v_readlane_b32 s18, v252, 58
	v_readlane_b32 s19, v252, 59
	s_mov_b64 s[20:21], 0
	s_nop 3
	global_load_dword v0, v153, s[18:19] sc1
	s_waitcnt vmcnt(0)
	v_cmp_eq_u32_e32 vcc, v0, v2
	s_and_saveexec_b64 s[18:19], vcc
	s_cbranch_execz .LBB0_394
	s_mov_b32 s59, 1
	s_branch .LBB0_387

.LBB0_397:
	s_or_b64 exec, exec, s[16:17]
.LBB0_398:
	s_or_b64 exec, exec, s[0:1]
	s_barrier

.LBB0_688:
	s_or_b64 exec, exec, s[16:17]
.LBB0_689:
	s_or_b64 exec, exec, s[10:11]
	s_barrier

.LBB0_805:
	s_or_b64 exec, exec, s[16:17]
.LBB0_806:
	s_or_b64 exec, exec, s[0:1]
	s_barrier
